# SEAM2 (P2->P3, WAR-only) grid barrier replaced by arrive counter + bounded wait before P3 first epilogue store
# speedup vs baseline: 1.0127x; 1.0127x over previous
; #define PG8_BAR __builtin_amdgcn_s_barrier()
; template <class Epi, class Sched, bool ALIGN_EPI = false, bool SP2 = false>
; __device__ __forceinline__ void gemm_phase(PG8_LAS unsigned char* lds, const Gemm g, const Sched& S, const Epi& E) {
;     const int tid = threadIdx.x, wid = __builtin_amdgcn_readfirstlane(tid >> 6), lane = tid & 63, wr = wid >> 2, wc = wid & 3, fr = lane & 15, fq = lane >> 4;
;     const int K = g.K, nt = K / BK;
;     unsigned voffA[2], voffB[2];
; #pragma unroll
;     for (int i = 0; i < 2; ++i) { int R, C; stage_rc(tid * 16 + i * 8192, R, C); const int Rb = Epi::PERM ? ((R & ~31) + perm32(R & 31)) : R;
;         voffA[i] = (unsigned)(R * K + C) * 2u; voffB[i] = (unsigned)(Rb * K + C) * 2u; }
;     const size_t kstep = (size_t)(BK * 2);
;     const size_t hstep = (size_t)HALF * K * 2;
;     const size_t tstep = 2 * hstep;
;     const unsigned ldsw = (unsigned)wid * 1024u;
;     const int aoff = lds_byte(wr * 64 + fr, fq * 8), boff = lds_byte(wc * 32 + fr, fq * 8);
;     ...
;     Unit cur, nxt; int ui = 0;
;     if (!S.next(0, cur)) return;
;     f32x4 acc[2][2][4][2];
; #pragma unroll
;     for (int a = 0; a < 2; ++a)
; #pragma unroll
;         for (int b = 0; b < 2; ++b)
; #pragma unroll
;             for (int m = 0; m < 4; ++m)
; #pragma unroll
;                 for (int n = 0; n < 2; ++n) acc[a][b][m][n] = (f32x4){0.f, 0.f, 0.f, 0.f};
;     bf16x8 At[4][2], B0[2][2], B1[2][2];
;     const char* cA = (const char*)g.A + (size_t)cur.pm * tstep; const char* cB = (const char*)g.Bt + (size_t)cur.pn * tstep;
;     S.a_ready(cur);
;     if constexpr (SP2) {
;         PG8_STAGE(PG8_SB(0, 0), cB, voffB); PG8_STAGE(PG8_SB(0, 1), cB + hstep, voffB); PG8_STAGE(PG8_SA(0, 0), cA, voffA); PG8_STAGE(PG8_SA(0, 1), cA + hstep, voffA);
;         if (wr == 1) PG8_BAR;
;         PG8_WAIT_V(2); PG8_BAR;
;         PG8_STAGE(PG8_SB(1, 0), cB + kstep, voffB); PG8_STAGE(PG8_SA(1, 0), cA + kstep, voffA); PG8_STAGE(PG8_SB(1, 1), cB + hstep + kstep, voffB);
;         PG8_WAIT_V(6); PG8_BAR;
;     } else {
; __global__ void __launch_bounds__(512, 2) fwd_megakernel(Args a) {
;     ...
;     SEAM(2);
;     if (IN(3)) {
;         pg8::Gemm g{(const u16*)(ws + WS_H), (const u16*)(ws + WS_WT), TT, 4096, 1024}; DefOrder S; S.base.init(48 * 256, 4096, G, bx);
;         EpiZ E{1, ws, dout, P.lbl}; pg8::gemm_phase<EpiZ, DefOrder, true, true>(lds, g, S, E); }
.LBB0_263:
	s_cmp_gt_i32 s83, 3
	s_cselect_b64 s[0:1], -1, 0
	s_and_b64 s[4:5], s[30:31], s[0:1]
	s_andn2_b64 vcc, exec, s[4:5]
	s_cbranch_vccnz .LBB0_317
	s_waitcnt vmcnt(0) lgkmcnt(0)
	s_barrier
	s_mov_b64 s[4:5], exec
	v_readlane_b32 s6, v248, 2
	v_readlane_b32 s7, v248, 3
	s_and_b64 s[6:7], s[4:5], s[6:7]
	s_mov_b64 exec, s[6:7]
	s_cbranch_execz .Lwar_arrived
	s_add_u32 s8, s78, 0x1f03800
	s_addc_u32 s9, s79, 0
	v_mov_b32_e32 v0, 0
	v_mov_b32_e32 v1, 1
	global_atomic_add v0, v1, s[8:9]
.Lwar_arrived:
	s_mov_b64 exec, s[4:5]
.LBB0_317:
	s_add_u32 s98, s78, 0x1f03800
	s_addc_u32 s99, s79, 0
	s_mov_b32 s100, 0
	s_cmp_lt_i32 s82, 4
	s_cselect_b64 s[4:5], -1, 0
	s_and_b64 s[4:5], s[4:5], s[0:1]
	s_andn2_b64 vcc, exec, s[4:5]
	s_cbranch_vccnz .LBB0_350
	s_cmpk_gt_i32 s2, 0x2ff
	v_readfirstlane_b32 s1, v188
	s_cbranch_scc1 .LBB0_350
	s_waitcnt vmcnt(0)
	v_lshrrev_b32_e32 v0, 5, v188
	v_lshrrev_b32_e32 v2, 1, v188
	v_and_b32_e32 v0, 4, v0
	v_bfe_u32 v1, v188, 2, 2
	v_and_b32_e32 v2, 24, v2
	v_or3_b32 v0, v0, v1, v2
	v_lshlrev_b32_e32 v1, 4, v188
	v_add_u32_e32 v8, 0x2000, v1
	v_lshrrev_b32_e32 v2, 7, v8
	s_movk_i32 s0, 0xe0
	v_and_b32_e32 v4, 32, v188
	v_and_or_b32 v3, v2, s0, v0
	v_bitop3_b32 v9, v1, v4, 48 bitop3:0x6c
	v_and_b32_e32 v10, 64, v188
	v_bfe_u32 v11, v188, 2, 4
	s_movk_i32 s0, 0xf0
	v_or_b32_e32 v1, v9, v10
	v_and_or_b32 v2, v2, s0, v11
	s_add_u32 s48, s78, 0x2000000
	v_lshl_or_b32 v130, v2, 11, v1
	v_lshrrev_b32_e32 v2, 3, v188
	s_movk_i32 s0, 0x60
	s_addc_u32 s49, s79, 0
	v_and_or_b32 v0, v2, s0, v0
	s_movk_i32 s0, 0x70
	s_ashr_i32 s51, s2, 31
	v_lshl_or_b32 v132, v0, 11, v1
	v_and_or_b32 v0, v2, s0, v11
	s_lshr_b32 s0, s51, 29
	s_add_i32 s0, s2, s0
	s_lshr_b32 s9, s1, 6
	s_ashr_i32 s6, s0, 3
	s_and_b32 s0, s0, -8
	s_lshr_b32 s8, s1, 8
	s_lshl_b32 s50, s9, 10
	s_sub_i32 s0, s2, s0
	s_cmp_lt_i32 s0, 0
	s_movk_i32 s52, 0x61
	s_cselect_b32 s7, s52, 0x60
	s_mul_i32 s0, s0, s7
	s_add_i32 s0, s0, s6
	s_ashr_i32 s6, s0, 31
	s_lshr_b32 s6, s6, 25
	s_add_i32 s6, s0, s6
	s_ashr_i32 s7, s6, 7
	s_and_b32 s6, s6, 0xffffff80
	s_sub_i32 s6, s0, s6
	s_bfe_i32 s0, s6, 0x80000
	s_bfe_u32 s0, s0, 0x3000c
	s_add_i32 s10, s6, s0
	s_bfe_i32 s0, s10, 0x80000
	s_and_b32 s10, s10, 0xf8
	s_sub_i32 s6, s6, s10
	s_lshl_b32 s7, s7, 3
	s_sext_i32_i8 s6, s6
	s_add_i32 s7, s7, s6
	s_mul_hi_i32 s6, s7, 0x2aaaaaab
	s_lshr_b32 s10, s6, 31
	s_add_i32 s6, s6, s10
	s_lshl_b32 s10, s6, 3
	s_mul_i32 s6, s6, 6
	s_sext_i32_i16 s0, s0
	s_sub_i32 s6, s7, s6
	s_lshr_b32 s0, s0, 3
	s_add_i32 s40, s10, s6
	s_ashr_i32 s41, s40, 31
	s_bfe_i64 s[10:11], s[0:1], 0x100000
	s_lshl_b64 s[6:7], s[40:41], 19
	s_lshl_b64 s[10:11], s[10:11], 19
	s_add_u32 s44, s78, s10
	s_addc_u32 s45, s79, s11
	s_add_i32 s53, s50, 0
	s_add_i32 m0, s53, 0x10000
	v_lshl_or_b32 v128, v3, 11, v1
	global_load_lds_dwordx4 v132, s[44:45]
	s_add_i32 m0, s53, 0x12000
	s_add_u32 s10, s44, 0x40000
	global_load_lds_dwordx4 v128, s[44:45]
	s_addc_u32 s11, s45, 0
	s_add_i32 m0, s53, 0x14000
	v_lshl_or_b32 v134, v0, 11, v1
	global_load_lds_dwordx4 v132, s[10:11]
	s_add_i32 m0, s53, 0x16000
	s_add_u32 s42, s48, s6
	s_addc_u32 s43, s49, s7
	s_waitcnt lgkmcnt(0)
	s_add_i32 s58, s53, 0x2000
	global_load_lds_dwordx4 v128, s[10:11]
	s_mov_b32 m0, s53
	s_add_u32 s6, s42, 0x40000
	global_load_lds_dwordx4 v134, s[42:43]
	s_mov_b32 m0, s58
	s_addc_u32 s7, s43, 0
	s_add_i32 s59, s53, 0x4000
	global_load_lds_dwordx4 v130, s[42:43]
	s_mov_b32 m0, s59
	s_add_i32 s60, s53, 0x6000
	global_load_lds_dwordx4 v134, s[6:7]
	s_mov_b32 m0, s60
	v_mov_b32_e32 v137, 0
	global_load_lds_dwordx4 v130, s[6:7]
	v_mov_b32_e32 v133, v137
	v_mov_b32_e32 v129, v137
	v_mov_b32_e32 v135, v137
	v_mov_b32_e32 v131, v137
	s_cmp_eq_u32 s8, 1
	s_movk_i32 s61, 0x2000
	s_mov_b32 s62, 0
	v_lshl_add_u64 v[6:7], s[44:45], 0, v[132:133]
	v_lshl_add_u64 v[2:3], s[44:45], 0, v[128:129]
	v_lshl_add_u64 v[0:1], s[42:43], 0, v[134:135]
	s_cselect_b64 s[6:7], -1, 0
	s_cmp_lg_u32 s8, 1
	v_lshl_add_u64 v[4:5], s[42:43], 0, v[130:131]
	s_cbranch_scc1 .LBB0_321
	s_barrier

; #define PG8_BAR __builtin_amdgcn_s_barrier()
; template <class Epi, class Sched, bool ALIGN_EPI = false, bool SP2 = false>
; __device__ __forceinline__ void gemm_phase(PG8_LAS unsigned char* lds, const Gemm g, const Sched& S, const Epi& E) {
;     ...
;         if constexpr (ALIGN_EPI) { if (wr == 0) PG8_BAR; }
;         if constexpr (!Epi::AFTER_DRAIN) { E(acc, cur, wr, wc, fr, fq); S.done(cur); }
.LBB0_330:
	s_cmp_eq_u32 s100, -1
	s_cbranch_scc1 .Lwar_ok
	v_mov_b32_e32 v240, 0
.Lwar_spin:
	global_load_dword v241, v240, s[98:99] sc1
	s_waitcnt vmcnt(0)
	v_readfirstlane_b32 s101, v241
	s_add_u32 s100, s100, 1
	s_nop 3
	s_cmp_ge_u32 s101, 0x100
	s_cbranch_scc1 .Lwar_done
	s_cmp_gt_u32 s100, 0x400000
	s_cbranch_scc1 .Lwar_done
	s_sleep 2
	s_branch .Lwar_spin
.Lwar_done:
	s_mov_b32 s100, -1

; __global__ void __launch_bounds__(512, 2) fwd_megakernel(Args a) {
;     extern __shared__ __attribute__((aligned(16))) unsigned char lds_raw[];
	.amdhsa_kernel _Z14fwd_megakernel4Args
		.amdhsa_group_segment_fixed_size 0
		.amdhsa_private_segment_fixed_size 0
		.amdhsa_kernarg_size 360
		.amdhsa_user_sgpr_count 2
		.amdhsa_user_sgpr_dispatch_ptr 0
		.amdhsa_user_sgpr_queue_ptr 0
		.amdhsa_user_sgpr_kernarg_segment_ptr 1
		.amdhsa_user_sgpr_dispatch_id 0
		.amdhsa_user_sgpr_kernarg_preload_length 0
		.amdhsa_user_sgpr_kernarg_preload_offset 0
		.amdhsa_user_sgpr_private_segment_size 0
		.amdhsa_uses_dynamic_stack 0
		.amdhsa_enable_private_segment 0
		.amdhsa_system_sgpr_workgroup_id_x 1
		.amdhsa_system_sgpr_workgroup_id_y 0
		.amdhsa_system_sgpr_workgroup_id_z 0
		.amdhsa_system_sgpr_workgroup_info 0
		.amdhsa_system_vgpr_workitem_id 2
		.amdhsa_next_free_vgpr 249
		.amdhsa_next_free_sgpr 102
		.amdhsa_accum_offset 252
		.amdhsa_reserve_vcc 1
		.amdhsa_float_round_mode_32 0
		.amdhsa_float_round_mode_16_64 0
		.amdhsa_float_denorm_mode_32 3
		.amdhsa_float_denorm_mode_16_64 3
		.amdhsa_dx10_clamp 1
		.amdhsa_ieee_mode 1
		.amdhsa_fp16_overflow 0
		.amdhsa_tg_split 0
		.amdhsa_exception_fp_ieee_invalid_op 0
		.amdhsa_exception_fp_denorm_src 0
		.amdhsa_exception_fp_ieee_div_zero 0
		.amdhsa_exception_fp_ieee_overflow 0
		.amdhsa_exception_fp_ieee_underflow 0
		.amdhsa_exception_fp_ieee_inexact 0
		.amdhsa_exception_int_div_zero 0
	.end_amdhsa_kernel

; __global__ void __launch_bounds__(512, 2) fwd_megakernel(Args a) {
amdhsa.kernels:
  - .agpr_count:     0
    .args:
      - .offset:         0
        .size:           104
        .value_kind:     by_value
      - .offset:         104
        .size:           4
        .value_kind:     hidden_block_count_x
      - .offset:         108
        .size:           4
        .value_kind:     hidden_block_count_y
      - .offset:         112
        .size:           4
        .value_kind:     hidden_block_count_z
      - .offset:         116
        .size:           2
        .value_kind:     hidden_group_size_x
      - .offset:         118
        .size:           2
        .value_kind:     hidden_group_size_y
      - .offset:         120
        .size:           2
        .value_kind:     hidden_group_size_z
      - .offset:         122
        .size:           2
        .value_kind:     hidden_remainder_x
      - .offset:         124
        .size:           2
        .value_kind:     hidden_remainder_y
      - .offset:         126
        .size:           2
        .value_kind:     hidden_remainder_z
      - .offset:         144
        .size:           8
        .value_kind:     hidden_global_offset_x
      - .offset:         152
        .size:           8
        .value_kind:     hidden_global_offset_y
      - .offset:         160
        .size:           8
        .value_kind:     hidden_global_offset_z
      - .offset:         168
        .size:           2
        .value_kind:     hidden_grid_dims
      - .offset:         192
        .size:           8
        .value_kind:     hidden_multigrid_sync_arg
      - .offset:         224
        .size:           4
        .value_kind:     hidden_dynamic_lds_size
    .group_segment_fixed_size: 0
    .kernarg_segment_align: 8
    .kernarg_segment_size: 360
    .language:       OpenCL C
    .language_version:
      - 2
      - 0
    .max_flat_workgroup_size: 512
    .name:           _Z14fwd_megakernel4Args
    .private_segment_fixed_size: 0
    .sgpr_count:     108
    .sgpr_spill_count: 6
    .symbol:         _Z14fwd_megakernel4Args.kd
    .uniform_work_group_size: 1
    .uses_dynamic_stack: false
    .vgpr_count:     249
    .vgpr_spill_count: 0
    .wavefront_size: 64
